# layer 1's weight transposes moved out of phase 0 into idle workgroups of layer 0's w_in phase (third GEMM round) and behind its GLU tiles; one shared hand-written transpose routine
# speedup vs baseline: 1.0332x; 1.0332x over previous
.Lp0w_entry:
	s_cmp_lg_u32 s36, 0
	s_cbranch_scc1 .LBB0_854
	s_cmpk_lt_u32 s63, 0x60
	s_cbranch_scc1 .LBB0_854
	s_add_u32 s38, s63, 0x558
	s_movk_i32 s39, 160
	s_movk_i32 s56, 2424
	s_branch .Lp0_common

.Lp0g_entry:
	s_cmp_lg_u32 s36, 0
	s_cbranch_scc1 .LBB0_854
	s_cmpk_lt_u32 s63, 0xc0
	s_cbranch_scc1 .LBB0_854
	s_add_u32 s38, s63, 0x8b8
	s_movk_i32 s39, 64
	s_movk_i32 s56, 2928
	s_branch .Lp0_common

.LBB0_801:
.Lp0_entry:
	s_mov_b32 s57, 0
	s_branch .Lp0_start
.Lp0_common:
	s_mov_b32 s57, 1
.Lp0_start:
	s_waitcnt vmcnt(0) lgkmcnt(0)
	s_barrier
	s_cmp_eq_u32 s57, 1
	s_cbranch_scc1 .Lp0_common2
	v_readlane_b32 s38, v237, 0
	v_readlane_b32 s39, v235, 55
	s_movk_i32 s56, 0x5b8
.Lp0_common2:
	s_cmp_ge_u32 s38, s56
	s_cbranch_scc1 .Lp0_done
	v_mov_b32_e32 v3, v206
	v_lshrrev_b32_e32 v4, 4, v3
	v_and_b32_e32 v5, 15, v3
	v_mul_u32_u24_e32 v6, 0x104, v4
	v_lshl_add_u32 v6, v5, 4, v6
	v_add_u32_e32 v7, 0x2080, v6
	v_add_u32_e32 v8, 0x4100, v6
	v_add_u32_e32 v9, 0x6180, v6
	v_mul_u32_u24_e32 v10, 0x820, v5
	v_lshl_add_u32 v10, v4, 2, v10
	v_add_u32_e32 v11, 0x80, v10
	s_mov_b32 s36, s38
	s_mov_b32 s37, 0
.Lp0_cnt:
	s_add_u32 s37, s37, 1
	s_add_u32 s38, s38, s39
	s_cmp_lt_u32 s38, s56
	s_cbranch_scc1 .Lp0_cnt
	s_cmp_ge_u32 s36, s56
	s_cbranch_scc1 .Lp0_pro0
	s_cmpk_ge_u32 s36, 0x5b8
	s_cselect_b32 s30, 1, 0
	s_mul_i32 s4, s30, 0x5b8
	s_sub_u32 s31, s36, s4
	s_cmpk_lt_u32 s31, 0x130
	s_cbranch_scc1 .Lp0_dec0_win
	s_cmpk_lt_u32 s31, 0x1b0
	s_cbranch_scc1 .Lp0_dec0_wout
	s_cmpk_lt_u32 s31, 0x3b0
	s_cbranch_scc1 .Lp0_dec0_w1
	s_cmpk_lt_u32 s31, 0x5b0
	s_cbranch_scc1 .Lp0_dec0_w2
	s_sub_u32 s31, s31, 0x5b0
	s_lshr_b32 s34, s31, 2
	s_and_b32 s35, s31, 3
	v_readlane_b32 s6, v237, 51
	v_readlane_b32 s7, v237, 52
	s_mul_i32 s4, s30, 0x40000
	s_add_u32 s6, s6, s4
	s_addc_u32 s7, s7, 0
	s_add_u32 s44, s96, 0x2d80000
	s_addc_u32 s45, s97, 0
	s_mul_i32 s4, s30, 0x20000
	s_movk_i32 s42, 0x400
	s_movk_i32 s46, 0x200
	s_movk_i32 s5, 0x100
	s_branch .Lp0_dec0_join
.Lp0_dec0_win:
	s_mul_hi_u32 s34, s31, 0x6bca1b0
	s_mul_i32 s4, s34, 38
	s_sub_u32 s35, s31, s4
	v_readlane_b32 s6, v237, 15
	v_readlane_b32 s7, v237, 16
	s_mul_i32 s4, s30, 0x910000
	s_add_u32 s6, s6, s4
	s_addc_u32 s7, s7, 0
	s_mov_b32 s44, s96
	s_mov_b32 s45, s97
	s_mul_i32 s4, s30, 0x4c0000
	s_movk_i32 s42, 0x2440
	s_movk_i32 s46, 0x800
	s_movk_i32 s5, 0x910
	s_branch .Lp0_dec0_join
.Lp0_dec0_wout:
	s_sub_u32 s31, s31, 0x130
	s_lshr_b32 s34, s31, 4
	s_and_b32 s35, s31, 15
	v_readlane_b32 s6, v237, 55
	v_readlane_b32 s7, v237, 56
	s_mul_i32 s4, s30, 0x400000
	s_add_u32 s6, s6, s4
	s_addc_u32 s7, s7, 0
	s_add_u32 s44, s96, 0x980000
	s_addc_u32 s45, s97, 0
	s_mul_i32 s4, s30, 0x200000
	s_movk_i32 s42, 0x1000
	s_movk_i32 s46, 0x800
	s_movk_i32 s5, 0x400
	s_branch .Lp0_dec0_join
.Lp0_dec0_w1:
	s_sub_u32 s31, s31, 0x1b0
	s_lshr_b32 s34, s31, 6
	s_and_b32 s35, s31, 63
	v_readlane_b32 s6, v237, 1
	v_readlane_b32 s7, v237, 2
	s_mul_i32 s4, s30, 0x1000000
	s_add_u32 s6, s6, s4
	s_addc_u32 s7, s7, 0
	s_add_u32 s44, s96, 0xd80000
	s_addc_u32 s45, s97, 0
	s_mul_i32 s4, s30, 0x800000
	s_movk_i32 s42, 0x4000
	s_movk_i32 s46, 0x800
	s_movk_i32 s5, 0x1000
	s_branch .Lp0_dec0_join
.Lp0_dec0_w2:
	s_sub_u32 s31, s31, 0x3b0
	s_lshr_b32 s34, s31, 4
	s_and_b32 s35, s31, 15
	v_readlane_b32 s6, v237, 3
	v_readlane_b32 s7, v237, 4
	s_mul_i32 s4, s30, 0x1000000
	s_add_u32 s6, s6, s4
	s_addc_u32 s7, s7, 0
	s_add_u32 s44, s96, 0x1d80000
	s_addc_u32 s45, s97, 0
	s_mul_i32 s4, s30, 0x800000
	s_movk_i32 s42, 0x1000
	s_movk_i32 s46, 0x2000
	s_movk_i32 s5, 0x400
.Lp0_dec0_join:
	s_add_u32 s44, s44, s4
	s_addc_u32 s45, s45, 0
	s_lshl_b32 s30, s34, 7
	s_mul_i32 s4, s30, s42
	s_lshl_b32 s31, s35, 8
	s_add_u32 s4, s4, s31
	s_add_u32 s40, s6, s4
	s_addc_u32 s41, s7, 0
	s_lshl_b32 s31, s35, 6
	s_sub_i32 s31, s5, s31
	s_max_i32 s31, s31, 0
	s_lshr_b32 s31, s31, 2
	s_min_u32 s43, s31, 16
	s_lshl_b32 s31, s35, 6
	s_mul_i32 s4, s31, s46
	s_lshl_b32 s30, s30, 1
	s_add_u32 s4, s4, s30
	s_add_u32 s44, s44, s4
	s_addc_u32 s45, s45, 0
	v_mov_b32_e32 v20, 0
	v_mov_b32_e32 v21, 0
	v_mov_b32_e32 v22, 0
	v_mov_b32_e32 v23, 0
	v_mov_b32_e32 v24, 0
	v_mov_b32_e32 v25, 0
	v_mov_b32_e32 v26, 0
	v_mov_b32_e32 v27, 0
	v_mov_b32_e32 v28, 0
	v_mov_b32_e32 v29, 0
	v_mov_b32_e32 v30, 0
	v_mov_b32_e32 v31, 0
	v_mov_b32_e32 v32, 0
	v_mov_b32_e32 v33, 0
	v_mov_b32_e32 v34, 0
	v_mov_b32_e32 v35, 0
	v_mul_lo_u32 v12, v4, s42
	v_lshl_add_u32 v12, v5, 4, v12
	s_lshl_b32 s4, s42, 5
	v_cmp_gt_u32_e32 vcc, s43, v5
	s_mov_b64 s[34:35], exec
	s_and_b64 exec, exec, vcc
	global_load_dwordx4 v[20:23], v12, s[40:41]
	v_add_u32_e32 v12, s4, v12
	global_load_dwordx4 v[24:27], v12, s[40:41]
	v_add_u32_e32 v12, s4, v12
	global_load_dwordx4 v[28:31], v12, s[40:41]
	v_add_u32_e32 v12, s4, v12
	global_load_dwordx4 v[32:35], v12, s[40:41]
	s_mov_b64 exec, s[34:35]
	s_add_u32 s36, s36, s39
.Lp0_pro0:
	s_cmp_ge_u32 s36, s56
	s_cbranch_scc1 .Lp0_pro1
	s_cmpk_ge_u32 s36, 0x5b8
	s_cselect_b32 s30, 1, 0
	s_mul_i32 s4, s30, 0x5b8
	s_sub_u32 s31, s36, s4
	s_cmpk_lt_u32 s31, 0x130
	s_cbranch_scc1 .Lp0_dec1_win
	s_cmpk_lt_u32 s31, 0x1b0
	s_cbranch_scc1 .Lp0_dec1_wout
	s_cmpk_lt_u32 s31, 0x3b0
	s_cbranch_scc1 .Lp0_dec1_w1
	s_cmpk_lt_u32 s31, 0x5b0
	s_cbranch_scc1 .Lp0_dec1_w2
	s_sub_u32 s31, s31, 0x5b0
	s_lshr_b32 s34, s31, 2
	s_and_b32 s35, s31, 3
	v_readlane_b32 s6, v237, 51
	v_readlane_b32 s7, v237, 52
	s_mul_i32 s4, s30, 0x40000
	s_add_u32 s6, s6, s4
	s_addc_u32 s7, s7, 0
	s_add_u32 s52, s96, 0x2d80000
	s_addc_u32 s53, s97, 0
	s_mul_i32 s4, s30, 0x20000
	s_movk_i32 s50, 0x400
	s_movk_i32 s54, 0x200
	s_movk_i32 s5, 0x100
	s_branch .Lp0_dec1_join
.Lp0_dec1_win:
	s_mul_hi_u32 s34, s31, 0x6bca1b0
	s_mul_i32 s4, s34, 38
	s_sub_u32 s35, s31, s4
	v_readlane_b32 s6, v237, 15
	v_readlane_b32 s7, v237, 16
	s_mul_i32 s4, s30, 0x910000
	s_add_u32 s6, s6, s4
	s_addc_u32 s7, s7, 0
	s_mov_b32 s52, s96
	s_mov_b32 s53, s97
	s_mul_i32 s4, s30, 0x4c0000
	s_movk_i32 s50, 0x2440
	s_movk_i32 s54, 0x800
	s_movk_i32 s5, 0x910
	s_branch .Lp0_dec1_join
.Lp0_dec1_wout:
	s_sub_u32 s31, s31, 0x130
	s_lshr_b32 s34, s31, 4
	s_and_b32 s35, s31, 15
	v_readlane_b32 s6, v237, 55
	v_readlane_b32 s7, v237, 56
	s_mul_i32 s4, s30, 0x400000
	s_add_u32 s6, s6, s4
	s_addc_u32 s7, s7, 0
	s_add_u32 s52, s96, 0x980000
	s_addc_u32 s53, s97, 0
	s_mul_i32 s4, s30, 0x200000
	s_movk_i32 s50, 0x1000
	s_movk_i32 s54, 0x800
	s_movk_i32 s5, 0x400
	s_branch .Lp0_dec1_join
.Lp0_dec1_w1:
	s_sub_u32 s31, s31, 0x1b0
	s_lshr_b32 s34, s31, 6
	s_and_b32 s35, s31, 63
	v_readlane_b32 s6, v237, 1
	v_readlane_b32 s7, v237, 2
	s_mul_i32 s4, s30, 0x1000000
	s_add_u32 s6, s6, s4
	s_addc_u32 s7, s7, 0
	s_add_u32 s52, s96, 0xd80000
	s_addc_u32 s53, s97, 0
	s_mul_i32 s4, s30, 0x800000
	s_movk_i32 s50, 0x4000
	s_movk_i32 s54, 0x800
	s_movk_i32 s5, 0x1000
	s_branch .Lp0_dec1_join
.Lp0_dec1_w2:
	s_sub_u32 s31, s31, 0x3b0
	s_lshr_b32 s34, s31, 4
	s_and_b32 s35, s31, 15
	v_readlane_b32 s6, v237, 3
	v_readlane_b32 s7, v237, 4
	s_mul_i32 s4, s30, 0x1000000
	s_add_u32 s6, s6, s4
	s_addc_u32 s7, s7, 0
	s_add_u32 s52, s96, 0x1d80000
	s_addc_u32 s53, s97, 0
	s_mul_i32 s4, s30, 0x800000
	s_movk_i32 s50, 0x1000
	s_movk_i32 s54, 0x2000
	s_movk_i32 s5, 0x400
.Lp0_dec1_join:
	s_add_u32 s52, s52, s4
	s_addc_u32 s53, s53, 0
	s_lshl_b32 s30, s34, 7
	s_mul_i32 s4, s30, s50
	s_lshl_b32 s31, s35, 8
	s_add_u32 s4, s4, s31
	s_add_u32 s48, s6, s4
	s_addc_u32 s49, s7, 0
	s_lshl_b32 s31, s35, 6
	s_sub_i32 s31, s5, s31
	s_max_i32 s31, s31, 0
	s_lshr_b32 s31, s31, 2
	s_min_u32 s51, s31, 16
	s_lshl_b32 s31, s35, 6
	s_mul_i32 s4, s31, s54
	s_lshl_b32 s30, s30, 1
	s_add_u32 s4, s4, s30
	s_add_u32 s52, s52, s4
	s_addc_u32 s53, s53, 0
	v_mov_b32_e32 v36, 0
	v_mov_b32_e32 v37, 0
	v_mov_b32_e32 v38, 0
	v_mov_b32_e32 v39, 0
	v_mov_b32_e32 v40, 0
	v_mov_b32_e32 v41, 0
	v_mov_b32_e32 v42, 0
	v_mov_b32_e32 v43, 0
	v_mov_b32_e32 v44, 0
	v_mov_b32_e32 v45, 0
	v_mov_b32_e32 v46, 0
	v_mov_b32_e32 v47, 0
	v_mov_b32_e32 v48, 0
	v_mov_b32_e32 v49, 0
	v_mov_b32_e32 v50, 0
	v_mov_b32_e32 v51, 0
	v_mul_lo_u32 v12, v4, s50
	v_lshl_add_u32 v12, v5, 4, v12
	s_lshl_b32 s4, s50, 5
	v_cmp_gt_u32_e32 vcc, s51, v5
	s_mov_b64 s[34:35], exec
	s_and_b64 exec, exec, vcc
	global_load_dwordx4 v[36:39], v12, s[48:49]
	v_add_u32_e32 v12, s4, v12
	global_load_dwordx4 v[40:43], v12, s[48:49]
	v_add_u32_e32 v12, s4, v12
	global_load_dwordx4 v[44:47], v12, s[48:49]
	v_add_u32_e32 v12, s4, v12
	global_load_dwordx4 v[48:51], v12, s[48:49]
	s_mov_b64 exec, s[34:35]
	s_add_u32 s36, s36, s39
.Lp0_pro1:
	s_cmp_ge_u32 s36, s56
	s_cbranch_scc1 .Lp0_pro2
	s_cmpk_ge_u32 s36, 0x5b8
	s_cselect_b32 s30, 1, 0
	s_mul_i32 s4, s30, 0x5b8
	s_sub_u32 s31, s36, s4
	s_cmpk_lt_u32 s31, 0x130
	s_cbranch_scc1 .Lp0_dec2_win
	s_cmpk_lt_u32 s31, 0x1b0
	s_cbranch_scc1 .Lp0_dec2_wout
	s_cmpk_lt_u32 s31, 0x3b0
	s_cbranch_scc1 .Lp0_dec2_w1
	s_cmpk_lt_u32 s31, 0x5b0
	s_cbranch_scc1 .Lp0_dec2_w2
	s_sub_u32 s31, s31, 0x5b0
	s_lshr_b32 s34, s31, 2
	s_and_b32 s35, s31, 3
	v_readlane_b32 s6, v237, 51
	v_readlane_b32 s7, v237, 52
	s_mul_i32 s4, s30, 0x40000
	s_add_u32 s6, s6, s4
	s_addc_u32 s7, s7, 0
	s_add_u32 s12, s96, 0x2d80000
	s_addc_u32 s13, s97, 0
	s_mul_i32 s4, s30, 0x20000
	s_movk_i32 s10, 0x400
	s_movk_i32 s14, 0x200
	s_movk_i32 s5, 0x100
	s_branch .Lp0_dec2_join
.Lp0_dec2_win:
	s_mul_hi_u32 s34, s31, 0x6bca1b0
	s_mul_i32 s4, s34, 38
	s_sub_u32 s35, s31, s4
	v_readlane_b32 s6, v237, 15
	v_readlane_b32 s7, v237, 16
	s_mul_i32 s4, s30, 0x910000
	s_add_u32 s6, s6, s4
	s_addc_u32 s7, s7, 0
	s_mov_b32 s12, s96
	s_mov_b32 s13, s97
	s_mul_i32 s4, s30, 0x4c0000
	s_movk_i32 s10, 0x2440
	s_movk_i32 s14, 0x800
	s_movk_i32 s5, 0x910
	s_branch .Lp0_dec2_join
.Lp0_dec2_wout:
	s_sub_u32 s31, s31, 0x130
	s_lshr_b32 s34, s31, 4
	s_and_b32 s35, s31, 15
	v_readlane_b32 s6, v237, 55
	v_readlane_b32 s7, v237, 56
	s_mul_i32 s4, s30, 0x400000
	s_add_u32 s6, s6, s4
	s_addc_u32 s7, s7, 0
	s_add_u32 s12, s96, 0x980000
	s_addc_u32 s13, s97, 0
	s_mul_i32 s4, s30, 0x200000
	s_movk_i32 s10, 0x1000
	s_movk_i32 s14, 0x800
	s_movk_i32 s5, 0x400
	s_branch .Lp0_dec2_join
.Lp0_dec2_w1:
	s_sub_u32 s31, s31, 0x1b0
	s_lshr_b32 s34, s31, 6
	s_and_b32 s35, s31, 63
	v_readlane_b32 s6, v237, 1
	v_readlane_b32 s7, v237, 2
	s_mul_i32 s4, s30, 0x1000000
	s_add_u32 s6, s6, s4
	s_addc_u32 s7, s7, 0
	s_add_u32 s12, s96, 0xd80000
	s_addc_u32 s13, s97, 0
	s_mul_i32 s4, s30, 0x800000
	s_movk_i32 s10, 0x4000
	s_movk_i32 s14, 0x800
	s_movk_i32 s5, 0x1000
	s_branch .Lp0_dec2_join
.Lp0_dec2_w2:
	s_sub_u32 s31, s31, 0x3b0
	s_lshr_b32 s34, s31, 4
	s_and_b32 s35, s31, 15
	v_readlane_b32 s6, v237, 3
	v_readlane_b32 s7, v237, 4
	s_mul_i32 s4, s30, 0x1000000
	s_add_u32 s6, s6, s4
	s_addc_u32 s7, s7, 0
	s_add_u32 s12, s96, 0x1d80000
	s_addc_u32 s13, s97, 0
	s_mul_i32 s4, s30, 0x800000
	s_movk_i32 s10, 0x1000
	s_movk_i32 s14, 0x2000
	s_movk_i32 s5, 0x400
.Lp0_dec2_join:
	s_add_u32 s12, s12, s4
	s_addc_u32 s13, s13, 0
	s_lshl_b32 s30, s34, 7
	s_mul_i32 s4, s30, s10
	s_lshl_b32 s31, s35, 8
	s_add_u32 s4, s4, s31
	s_add_u32 s8, s6, s4
	s_addc_u32 s9, s7, 0
	s_lshl_b32 s31, s35, 6
	s_sub_i32 s31, s5, s31
	s_max_i32 s31, s31, 0
	s_lshr_b32 s31, s31, 2
	s_min_u32 s11, s31, 16
	s_lshl_b32 s31, s35, 6
	s_mul_i32 s4, s31, s14
	s_lshl_b32 s30, s30, 1
	s_add_u32 s4, s4, s30
	s_add_u32 s12, s12, s4
	s_addc_u32 s13, s13, 0
	v_mov_b32_e32 v52, 0
	v_mov_b32_e32 v53, 0
	v_mov_b32_e32 v54, 0
	v_mov_b32_e32 v55, 0
	v_mov_b32_e32 v56, 0
	v_mov_b32_e32 v57, 0
	v_mov_b32_e32 v58, 0
	v_mov_b32_e32 v59, 0
	v_mov_b32_e32 v60, 0
	v_mov_b32_e32 v61, 0
	v_mov_b32_e32 v62, 0
	v_mov_b32_e32 v63, 0
	v_mov_b32_e32 v64, 0
	v_mov_b32_e32 v65, 0
	v_mov_b32_e32 v66, 0
	v_mov_b32_e32 v67, 0
	v_mul_lo_u32 v12, v4, s10
	v_lshl_add_u32 v12, v5, 4, v12
	s_lshl_b32 s4, s10, 5
	v_cmp_gt_u32_e32 vcc, s11, v5
	s_mov_b64 s[34:35], exec
	s_and_b64 exec, exec, vcc
	global_load_dwordx4 v[52:55], v12, s[8:9]
	v_add_u32_e32 v12, s4, v12
	global_load_dwordx4 v[56:59], v12, s[8:9]
	v_add_u32_e32 v12, s4, v12
	global_load_dwordx4 v[60:63], v12, s[8:9]
	v_add_u32_e32 v12, s4, v12
	global_load_dwordx4 v[64:67], v12, s[8:9]
	s_mov_b64 exec, s[34:35]
	s_add_u32 s36, s36, s39
.Lp0_pro2:
	s_cmp_ge_u32 s37, 3
	s_cbranch_scc1 .Lp0_w0
	s_waitcnt vmcnt(0)
.Lp0_w0:
	s_waitcnt vmcnt(8)
	ds_write2_b32 v6, v20, v21 offset1:1
	ds_write2_b32 v6, v22, v23 offset0:2 offset1:3
	ds_write2_b32 v7, v24, v25 offset1:1
	ds_write2_b32 v7, v26, v27 offset0:2 offset1:3
	ds_write2_b32 v8, v28, v29 offset1:1
	ds_write2_b32 v8, v30, v31 offset0:2 offset1:3
	ds_write2_b32 v9, v32, v33 offset1:1
	ds_write2_b32 v9, v34, v35 offset0:2 offset1:3
	s_waitcnt lgkmcnt(0)
	s_barrier
	v_mul_lo_u32 v13, v4, s46
	v_lshl_add_u32 v13, v5, 4, v13
	s_lshl_b32 s4, s46, 5
	ds_read_b32 v68, v10 offset:0
	ds_read_b32 v69, v10 offset:260
	ds_read_b32 v70, v10 offset:520
	ds_read_b32 v71, v10 offset:780
	ds_read_b32 v72, v10 offset:1040
	ds_read_b32 v73, v10 offset:1300
	ds_read_b32 v74, v10 offset:1560
	ds_read_b32 v75, v10 offset:1820
	s_waitcnt lgkmcnt(0)
	v_cvt_pk_bf16_f32 v84, v68, v69
	v_cvt_pk_bf16_f32 v85, v70, v71
	v_cvt_pk_bf16_f32 v86, v72, v73
	v_cvt_pk_bf16_f32 v87, v74, v75
	global_store_dwordx4 v13, v[84:87], s[44:45]
	v_add_u32_e32 v13, s4, v13
	ds_read_b32 v68, v11 offset:0
	ds_read_b32 v69, v11 offset:260
	ds_read_b32 v70, v11 offset:520
	ds_read_b32 v71, v11 offset:780
	ds_read_b32 v72, v11 offset:1040
	ds_read_b32 v73, v11 offset:1300
	ds_read_b32 v74, v11 offset:1560
	ds_read_b32 v75, v11 offset:1820
	s_waitcnt lgkmcnt(0)
	v_cvt_pk_bf16_f32 v88, v68, v69
	v_cvt_pk_bf16_f32 v89, v70, v71
	v_cvt_pk_bf16_f32 v90, v72, v73
	v_cvt_pk_bf16_f32 v91, v74, v75
	global_store_dwordx4 v13, v[88:91], s[44:45]
	s_cmp_ge_u32 s36, s56
	s_cbranch_scc1 .Lp0_r0
	s_cmpk_ge_u32 s36, 0x5b8
	s_cselect_b32 s30, 1, 0
	s_mul_i32 s4, s30, 0x5b8
	s_sub_u32 s31, s36, s4
	s_cmpk_lt_u32 s31, 0x130
	s_cbranch_scc1 .Lp0_dec3_win
	s_cmpk_lt_u32 s31, 0x1b0
	s_cbranch_scc1 .Lp0_dec3_wout
	s_cmpk_lt_u32 s31, 0x3b0
	s_cbranch_scc1 .Lp0_dec3_w1
	s_cmpk_lt_u32 s31, 0x5b0
	s_cbranch_scc1 .Lp0_dec3_w2
	s_sub_u32 s31, s31, 0x5b0
	s_lshr_b32 s34, s31, 2
	s_and_b32 s35, s31, 3
	v_readlane_b32 s6, v237, 51
	v_readlane_b32 s7, v237, 52
	s_mul_i32 s4, s30, 0x40000
	s_add_u32 s6, s6, s4
	s_addc_u32 s7, s7, 0
	s_add_u32 s44, s96, 0x2d80000
	s_addc_u32 s45, s97, 0
	s_mul_i32 s4, s30, 0x20000
	s_movk_i32 s42, 0x400
	s_movk_i32 s46, 0x200
	s_movk_i32 s5, 0x100
	s_branch .Lp0_dec3_join

.Lp0_r0:
	s_sub_u32 s37, s37, 1
	s_cmp_eq_u32 s37, 0
	s_cbranch_scc1 .Lp0_done
	s_cmp_ge_u32 s37, 3
	s_cbranch_scc1 .Lp0_w1
	s_waitcnt vmcnt(0)
.Lp0_w1:
	s_waitcnt vmcnt(10)
	v_add_u32_e32 v68, 0x8200, v6
	ds_write2_b32 v68, v36, v37 offset1:1
	ds_write2_b32 v68, v38, v39 offset0:2 offset1:3
	v_add_u32_e32 v68, 0x8200, v7
	ds_write2_b32 v68, v40, v41 offset1:1
	ds_write2_b32 v68, v42, v43 offset0:2 offset1:3
	v_add_u32_e32 v68, 0x8200, v8
	ds_write2_b32 v68, v44, v45 offset1:1
	ds_write2_b32 v68, v46, v47 offset0:2 offset1:3
	v_add_u32_e32 v68, 0x8200, v9
	ds_write2_b32 v68, v48, v49 offset1:1
	ds_write2_b32 v68, v50, v51 offset0:2 offset1:3
	s_waitcnt lgkmcnt(0)
	s_barrier
	v_mul_lo_u32 v13, v4, s54
	v_lshl_add_u32 v13, v5, 4, v13
	s_lshl_b32 s4, s54, 5
	v_add_u32_e32 v83, 0x8200, v10
	ds_read_b32 v68, v83 offset:0
	ds_read_b32 v69, v83 offset:260
	ds_read_b32 v70, v83 offset:520
	ds_read_b32 v71, v83 offset:780
	ds_read_b32 v72, v83 offset:1040
	ds_read_b32 v73, v83 offset:1300
	ds_read_b32 v74, v83 offset:1560
	ds_read_b32 v75, v83 offset:1820
	s_waitcnt lgkmcnt(0)
	v_cvt_pk_bf16_f32 v84, v68, v69
	v_cvt_pk_bf16_f32 v85, v70, v71
	v_cvt_pk_bf16_f32 v86, v72, v73
	v_cvt_pk_bf16_f32 v87, v74, v75
	global_store_dwordx4 v13, v[84:87], s[52:53]
	v_add_u32_e32 v13, s4, v13
	v_add_u32_e32 v83, 0x8200, v11
	ds_read_b32 v68, v83 offset:0
	ds_read_b32 v69, v83 offset:260
	ds_read_b32 v70, v83 offset:520
	ds_read_b32 v71, v83 offset:780
	ds_read_b32 v72, v83 offset:1040
	ds_read_b32 v73, v83 offset:1300
	ds_read_b32 v74, v83 offset:1560
	ds_read_b32 v75, v83 offset:1820
	s_waitcnt lgkmcnt(0)
	v_cvt_pk_bf16_f32 v88, v68, v69
	v_cvt_pk_bf16_f32 v89, v70, v71
	v_cvt_pk_bf16_f32 v90, v72, v73
	v_cvt_pk_bf16_f32 v91, v74, v75
	global_store_dwordx4 v13, v[88:91], s[52:53]
	s_cmp_ge_u32 s36, s56
	s_cbranch_scc1 .Lp0_r1
	s_cmpk_ge_u32 s36, 0x5b8
	s_cselect_b32 s30, 1, 0
	s_mul_i32 s4, s30, 0x5b8
	s_sub_u32 s31, s36, s4
	s_cmpk_lt_u32 s31, 0x130
	s_cbranch_scc1 .Lp0_dec4_win
	s_cmpk_lt_u32 s31, 0x1b0
	s_cbranch_scc1 .Lp0_dec4_wout
	s_cmpk_lt_u32 s31, 0x3b0
	s_cbranch_scc1 .Lp0_dec4_w1
	s_cmpk_lt_u32 s31, 0x5b0
	s_cbranch_scc1 .Lp0_dec4_w2
	s_sub_u32 s31, s31, 0x5b0
	s_lshr_b32 s34, s31, 2
	s_and_b32 s35, s31, 3
	v_readlane_b32 s6, v237, 51
	v_readlane_b32 s7, v237, 52
	s_mul_i32 s4, s30, 0x40000
	s_add_u32 s6, s6, s4
	s_addc_u32 s7, s7, 0
	s_add_u32 s52, s96, 0x2d80000
	s_addc_u32 s53, s97, 0
	s_mul_i32 s4, s30, 0x20000
	s_movk_i32 s50, 0x400
	s_movk_i32 s54, 0x200
	s_movk_i32 s5, 0x100
	s_branch .Lp0_dec4_join

.Lp0_r1:
	s_sub_u32 s37, s37, 1
	s_cmp_eq_u32 s37, 0
	s_cbranch_scc1 .Lp0_done

.Lp0_w2:
	s_waitcnt vmcnt(12)
	ds_write2_b32 v6, v52, v53 offset1:1
	ds_write2_b32 v6, v54, v55 offset0:2 offset1:3
	ds_write2_b32 v7, v56, v57 offset1:1
	ds_write2_b32 v7, v58, v59 offset0:2 offset1:3
	ds_write2_b32 v8, v60, v61 offset1:1
	ds_write2_b32 v8, v62, v63 offset0:2 offset1:3
	ds_write2_b32 v9, v64, v65 offset1:1
	ds_write2_b32 v9, v66, v67 offset0:2 offset1:3
	s_waitcnt lgkmcnt(0)
	s_barrier
	v_mul_lo_u32 v13, v4, s14
	v_lshl_add_u32 v13, v5, 4, v13
	s_lshl_b32 s4, s14, 5
	ds_read_b32 v68, v10 offset:0
	ds_read_b32 v69, v10 offset:260
	ds_read_b32 v70, v10 offset:520
	ds_read_b32 v71, v10 offset:780
	ds_read_b32 v72, v10 offset:1040
	ds_read_b32 v73, v10 offset:1300
	ds_read_b32 v74, v10 offset:1560
	ds_read_b32 v75, v10 offset:1820
	s_waitcnt lgkmcnt(0)
	v_cvt_pk_bf16_f32 v84, v68, v69
	v_cvt_pk_bf16_f32 v85, v70, v71
	v_cvt_pk_bf16_f32 v86, v72, v73
	v_cvt_pk_bf16_f32 v87, v74, v75
	global_store_dwordx4 v13, v[84:87], s[12:13]
	v_add_u32_e32 v13, s4, v13
	ds_read_b32 v68, v11 offset:0
	ds_read_b32 v69, v11 offset:260
	ds_read_b32 v70, v11 offset:520
	ds_read_b32 v71, v11 offset:780
	ds_read_b32 v72, v11 offset:1040
	ds_read_b32 v73, v11 offset:1300
	ds_read_b32 v74, v11 offset:1560
	ds_read_b32 v75, v11 offset:1820
	s_waitcnt lgkmcnt(0)
	v_cvt_pk_bf16_f32 v88, v68, v69
	v_cvt_pk_bf16_f32 v89, v70, v71
	v_cvt_pk_bf16_f32 v90, v72, v73
	v_cvt_pk_bf16_f32 v91, v74, v75
	global_store_dwordx4 v13, v[88:91], s[12:13]
	s_cmp_ge_u32 s36, s56
	s_cbranch_scc1 .Lp0_r2
	s_cmpk_ge_u32 s36, 0x5b8
	s_cselect_b32 s30, 1, 0
	s_mul_i32 s4, s30, 0x5b8
	s_sub_u32 s31, s36, s4
	s_cmpk_lt_u32 s31, 0x130
	s_cbranch_scc1 .Lp0_dec5_win
	s_cmpk_lt_u32 s31, 0x1b0
	s_cbranch_scc1 .Lp0_dec5_wout
	s_cmpk_lt_u32 s31, 0x3b0
	s_cbranch_scc1 .Lp0_dec5_w1
	s_cmpk_lt_u32 s31, 0x5b0
	s_cbranch_scc1 .Lp0_dec5_w2
	s_sub_u32 s31, s31, 0x5b0
	s_lshr_b32 s34, s31, 2
	s_and_b32 s35, s31, 3
	v_readlane_b32 s6, v237, 51
	v_readlane_b32 s7, v237, 52
	s_mul_i32 s4, s30, 0x40000
	s_add_u32 s6, s6, s4
	s_addc_u32 s7, s7, 0
	s_add_u32 s12, s96, 0x2d80000
	s_addc_u32 s13, s97, 0
	s_mul_i32 s4, s30, 0x20000
	s_movk_i32 s10, 0x400
	s_movk_i32 s14, 0x200
	s_movk_i32 s5, 0x100
	s_branch .Lp0_dec5_join

.Lp0_w3:
	s_waitcnt vmcnt(12)
	v_add_u32_e32 v68, 0x8200, v6
	ds_write2_b32 v68, v20, v21 offset1:1
	ds_write2_b32 v68, v22, v23 offset0:2 offset1:3
	v_add_u32_e32 v68, 0x8200, v7
	ds_write2_b32 v68, v24, v25 offset1:1
	ds_write2_b32 v68, v26, v27 offset0:2 offset1:3
	v_add_u32_e32 v68, 0x8200, v8
	ds_write2_b32 v68, v28, v29 offset1:1
	ds_write2_b32 v68, v30, v31 offset0:2 offset1:3
	v_add_u32_e32 v68, 0x8200, v9
	ds_write2_b32 v68, v32, v33 offset1:1
	ds_write2_b32 v68, v34, v35 offset0:2 offset1:3
	s_waitcnt lgkmcnt(0)
	s_barrier
	v_mul_lo_u32 v13, v4, s46
	v_lshl_add_u32 v13, v5, 4, v13
	s_lshl_b32 s4, s46, 5
	v_add_u32_e32 v83, 0x8200, v10
	ds_read_b32 v68, v83 offset:0
	ds_read_b32 v69, v83 offset:260
	ds_read_b32 v70, v83 offset:520
	ds_read_b32 v71, v83 offset:780
	ds_read_b32 v72, v83 offset:1040
	ds_read_b32 v73, v83 offset:1300
	ds_read_b32 v74, v83 offset:1560
	ds_read_b32 v75, v83 offset:1820
	s_waitcnt lgkmcnt(0)
	v_cvt_pk_bf16_f32 v84, v68, v69
	v_cvt_pk_bf16_f32 v85, v70, v71
	v_cvt_pk_bf16_f32 v86, v72, v73
	v_cvt_pk_bf16_f32 v87, v74, v75
	global_store_dwordx4 v13, v[84:87], s[44:45]
	v_add_u32_e32 v13, s4, v13
	v_add_u32_e32 v83, 0x8200, v11
	ds_read_b32 v68, v83 offset:0
	ds_read_b32 v69, v83 offset:260
	ds_read_b32 v70, v83 offset:520
	ds_read_b32 v71, v83 offset:780
	ds_read_b32 v72, v83 offset:1040
	ds_read_b32 v73, v83 offset:1300
	ds_read_b32 v74, v83 offset:1560
	ds_read_b32 v75, v83 offset:1820
	s_waitcnt lgkmcnt(0)
	v_cvt_pk_bf16_f32 v88, v68, v69
	v_cvt_pk_bf16_f32 v89, v70, v71
	v_cvt_pk_bf16_f32 v90, v72, v73
	v_cvt_pk_bf16_f32 v91, v74, v75
	global_store_dwordx4 v13, v[88:91], s[44:45]
	s_cmp_ge_u32 s36, s56
	s_cbranch_scc1 .Lp0_r3
	s_cmpk_ge_u32 s36, 0x5b8
	s_cselect_b32 s30, 1, 0
	s_mul_i32 s4, s30, 0x5b8
	s_sub_u32 s31, s36, s4
	s_cmpk_lt_u32 s31, 0x130
	s_cbranch_scc1 .Lp0_dec6_win
	s_cmpk_lt_u32 s31, 0x1b0
	s_cbranch_scc1 .Lp0_dec6_wout
	s_cmpk_lt_u32 s31, 0x3b0
	s_cbranch_scc1 .Lp0_dec6_w1
	s_cmpk_lt_u32 s31, 0x5b0
	s_cbranch_scc1 .Lp0_dec6_w2
	s_sub_u32 s31, s31, 0x5b0
	s_lshr_b32 s34, s31, 2
	s_and_b32 s35, s31, 3
	v_readlane_b32 s6, v237, 51
	v_readlane_b32 s7, v237, 52
	s_mul_i32 s4, s30, 0x40000
	s_add_u32 s6, s6, s4
	s_addc_u32 s7, s7, 0
	s_add_u32 s44, s96, 0x2d80000
	s_addc_u32 s45, s97, 0
	s_mul_i32 s4, s30, 0x20000
	s_movk_i32 s42, 0x400
	s_movk_i32 s46, 0x200
	s_movk_i32 s5, 0x100
	s_branch .Lp0_dec6_join

.Lp0_w4:
	s_waitcnt vmcnt(12)
	ds_write2_b32 v6, v36, v37 offset1:1
	ds_write2_b32 v6, v38, v39 offset0:2 offset1:3
	ds_write2_b32 v7, v40, v41 offset1:1
	ds_write2_b32 v7, v42, v43 offset0:2 offset1:3
	ds_write2_b32 v8, v44, v45 offset1:1
	ds_write2_b32 v8, v46, v47 offset0:2 offset1:3
	ds_write2_b32 v9, v48, v49 offset1:1
	ds_write2_b32 v9, v50, v51 offset0:2 offset1:3
	s_waitcnt lgkmcnt(0)
	s_barrier
	v_mul_lo_u32 v13, v4, s54
	v_lshl_add_u32 v13, v5, 4, v13
	s_lshl_b32 s4, s54, 5
	ds_read_b32 v68, v10 offset:0
	ds_read_b32 v69, v10 offset:260
	ds_read_b32 v70, v10 offset:520
	ds_read_b32 v71, v10 offset:780
	ds_read_b32 v72, v10 offset:1040
	ds_read_b32 v73, v10 offset:1300
	ds_read_b32 v74, v10 offset:1560
	ds_read_b32 v75, v10 offset:1820
	s_waitcnt lgkmcnt(0)
	v_cvt_pk_bf16_f32 v84, v68, v69
	v_cvt_pk_bf16_f32 v85, v70, v71
	v_cvt_pk_bf16_f32 v86, v72, v73
	v_cvt_pk_bf16_f32 v87, v74, v75
	global_store_dwordx4 v13, v[84:87], s[52:53]
	v_add_u32_e32 v13, s4, v13
	ds_read_b32 v68, v11 offset:0
	ds_read_b32 v69, v11 offset:260
	ds_read_b32 v70, v11 offset:520
	ds_read_b32 v71, v11 offset:780
	ds_read_b32 v72, v11 offset:1040
	ds_read_b32 v73, v11 offset:1300
	ds_read_b32 v74, v11 offset:1560
	ds_read_b32 v75, v11 offset:1820
	s_waitcnt lgkmcnt(0)
	v_cvt_pk_bf16_f32 v88, v68, v69
	v_cvt_pk_bf16_f32 v89, v70, v71
	v_cvt_pk_bf16_f32 v90, v72, v73
	v_cvt_pk_bf16_f32 v91, v74, v75
	global_store_dwordx4 v13, v[88:91], s[52:53]
	s_cmp_ge_u32 s36, s56
	s_cbranch_scc1 .Lp0_r4
	s_cmpk_ge_u32 s36, 0x5b8
	s_cselect_b32 s30, 1, 0
	s_mul_i32 s4, s30, 0x5b8
	s_sub_u32 s31, s36, s4
	s_cmpk_lt_u32 s31, 0x130
	s_cbranch_scc1 .Lp0_dec7_win
	s_cmpk_lt_u32 s31, 0x1b0
	s_cbranch_scc1 .Lp0_dec7_wout
	s_cmpk_lt_u32 s31, 0x3b0
	s_cbranch_scc1 .Lp0_dec7_w1
	s_cmpk_lt_u32 s31, 0x5b0
	s_cbranch_scc1 .Lp0_dec7_w2
	s_sub_u32 s31, s31, 0x5b0
	s_lshr_b32 s34, s31, 2
	s_and_b32 s35, s31, 3
	v_readlane_b32 s6, v237, 51
	v_readlane_b32 s7, v237, 52
	s_mul_i32 s4, s30, 0x40000
	s_add_u32 s6, s6, s4
	s_addc_u32 s7, s7, 0
	s_add_u32 s52, s96, 0x2d80000
	s_addc_u32 s53, s97, 0
	s_mul_i32 s4, s30, 0x20000
	s_movk_i32 s50, 0x400
	s_movk_i32 s54, 0x200
	s_movk_i32 s5, 0x100
	s_branch .Lp0_dec7_join

.Lp0_w5:
	s_waitcnt vmcnt(12)
	v_add_u32_e32 v68, 0x8200, v6
	ds_write2_b32 v68, v52, v53 offset1:1
	ds_write2_b32 v68, v54, v55 offset0:2 offset1:3
	v_add_u32_e32 v68, 0x8200, v7
	ds_write2_b32 v68, v56, v57 offset1:1
	ds_write2_b32 v68, v58, v59 offset0:2 offset1:3
	v_add_u32_e32 v68, 0x8200, v8
	ds_write2_b32 v68, v60, v61 offset1:1
	ds_write2_b32 v68, v62, v63 offset0:2 offset1:3
	v_add_u32_e32 v68, 0x8200, v9
	ds_write2_b32 v68, v64, v65 offset1:1
	ds_write2_b32 v68, v66, v67 offset0:2 offset1:3
	s_waitcnt lgkmcnt(0)
	s_barrier
	v_mul_lo_u32 v13, v4, s14
	v_lshl_add_u32 v13, v5, 4, v13
	s_lshl_b32 s4, s14, 5
	v_add_u32_e32 v83, 0x8200, v10
	ds_read_b32 v68, v83 offset:0
	ds_read_b32 v69, v83 offset:260
	ds_read_b32 v70, v83 offset:520
	ds_read_b32 v71, v83 offset:780
	ds_read_b32 v72, v83 offset:1040
	ds_read_b32 v73, v83 offset:1300
	ds_read_b32 v74, v83 offset:1560
	ds_read_b32 v75, v83 offset:1820
	s_waitcnt lgkmcnt(0)
	v_cvt_pk_bf16_f32 v84, v68, v69
	v_cvt_pk_bf16_f32 v85, v70, v71
	v_cvt_pk_bf16_f32 v86, v72, v73
	v_cvt_pk_bf16_f32 v87, v74, v75
	global_store_dwordx4 v13, v[84:87], s[12:13]
	v_add_u32_e32 v13, s4, v13
	v_add_u32_e32 v83, 0x8200, v11
	ds_read_b32 v68, v83 offset:0
	ds_read_b32 v69, v83 offset:260
	ds_read_b32 v70, v83 offset:520
	ds_read_b32 v71, v83 offset:780
	ds_read_b32 v72, v83 offset:1040
	ds_read_b32 v73, v83 offset:1300
	ds_read_b32 v74, v83 offset:1560
	ds_read_b32 v75, v83 offset:1820
	s_waitcnt lgkmcnt(0)
	v_cvt_pk_bf16_f32 v88, v68, v69
	v_cvt_pk_bf16_f32 v89, v70, v71
	v_cvt_pk_bf16_f32 v90, v72, v73
	v_cvt_pk_bf16_f32 v91, v74, v75
	global_store_dwordx4 v13, v[88:91], s[12:13]
	s_cmp_ge_u32 s36, s56
	s_cbranch_scc1 .Lp0_r5
	s_cmpk_ge_u32 s36, 0x5b8
	s_cselect_b32 s30, 1, 0
	s_mul_i32 s4, s30, 0x5b8
	s_sub_u32 s31, s36, s4
	s_cmpk_lt_u32 s31, 0x130
	s_cbranch_scc1 .Lp0_dec8_win
	s_cmpk_lt_u32 s31, 0x1b0
	s_cbranch_scc1 .Lp0_dec8_wout
	s_cmpk_lt_u32 s31, 0x3b0
	s_cbranch_scc1 .Lp0_dec8_w1
	s_cmpk_lt_u32 s31, 0x5b0
	s_cbranch_scc1 .Lp0_dec8_w2
	s_sub_u32 s31, s31, 0x5b0
	s_lshr_b32 s34, s31, 2
	s_and_b32 s35, s31, 3
	v_readlane_b32 s6, v237, 51
	v_readlane_b32 s7, v237, 52
	s_mul_i32 s4, s30, 0x40000
	s_add_u32 s6, s6, s4
	s_addc_u32 s7, s7, 0
	s_add_u32 s12, s96, 0x2d80000
	s_addc_u32 s13, s97, 0
	s_mul_i32 s4, s30, 0x20000
	s_movk_i32 s10, 0x400
	s_movk_i32 s14, 0x200
	s_movk_i32 s5, 0x100
	s_branch .Lp0_dec8_join

.Lp0_w6:
	s_waitcnt vmcnt(12)
	ds_write2_b32 v6, v20, v21 offset1:1
	ds_write2_b32 v6, v22, v23 offset0:2 offset1:3
	ds_write2_b32 v7, v24, v25 offset1:1
	ds_write2_b32 v7, v26, v27 offset0:2 offset1:3
	ds_write2_b32 v8, v28, v29 offset1:1
	ds_write2_b32 v8, v30, v31 offset0:2 offset1:3
	ds_write2_b32 v9, v32, v33 offset1:1
	ds_write2_b32 v9, v34, v35 offset0:2 offset1:3
	s_waitcnt lgkmcnt(0)
	s_barrier
	v_mul_lo_u32 v13, v4, s46
	v_lshl_add_u32 v13, v5, 4, v13
	s_lshl_b32 s4, s46, 5
	ds_read_b32 v68, v10 offset:0
	ds_read_b32 v69, v10 offset:260
	ds_read_b32 v70, v10 offset:520
	ds_read_b32 v71, v10 offset:780
	ds_read_b32 v72, v10 offset:1040
	ds_read_b32 v73, v10 offset:1300
	ds_read_b32 v74, v10 offset:1560
	ds_read_b32 v75, v10 offset:1820
	s_waitcnt lgkmcnt(0)
	v_cvt_pk_bf16_f32 v84, v68, v69
	v_cvt_pk_bf16_f32 v85, v70, v71
	v_cvt_pk_bf16_f32 v86, v72, v73
	v_cvt_pk_bf16_f32 v87, v74, v75
	global_store_dwordx4 v13, v[84:87], s[44:45]
	v_add_u32_e32 v13, s4, v13
	ds_read_b32 v68, v11 offset:0
	ds_read_b32 v69, v11 offset:260
	ds_read_b32 v70, v11 offset:520
	ds_read_b32 v71, v11 offset:780
	ds_read_b32 v72, v11 offset:1040
	ds_read_b32 v73, v11 offset:1300
	ds_read_b32 v74, v11 offset:1560
	ds_read_b32 v75, v11 offset:1820
	s_waitcnt lgkmcnt(0)
	v_cvt_pk_bf16_f32 v88, v68, v69
	v_cvt_pk_bf16_f32 v89, v70, v71
	v_cvt_pk_bf16_f32 v90, v72, v73
	v_cvt_pk_bf16_f32 v91, v74, v75
	global_store_dwordx4 v13, v[88:91], s[44:45]
	s_cmp_ge_u32 s36, s56
	s_cbranch_scc1 .Lp0_r6
	s_cmpk_ge_u32 s36, 0x5b8
	s_cselect_b32 s30, 1, 0
	s_mul_i32 s4, s30, 0x5b8
	s_sub_u32 s31, s36, s4
	s_cmpk_lt_u32 s31, 0x130
	s_cbranch_scc1 .Lp0_dec9_win
	s_cmpk_lt_u32 s31, 0x1b0
	s_cbranch_scc1 .Lp0_dec9_wout
	s_cmpk_lt_u32 s31, 0x3b0
	s_cbranch_scc1 .Lp0_dec9_w1
	s_cmpk_lt_u32 s31, 0x5b0
	s_cbranch_scc1 .Lp0_dec9_w2
	s_sub_u32 s31, s31, 0x5b0
	s_lshr_b32 s34, s31, 2
	s_and_b32 s35, s31, 3
	v_readlane_b32 s6, v237, 51
	v_readlane_b32 s7, v237, 52
	s_mul_i32 s4, s30, 0x40000
	s_add_u32 s6, s6, s4
	s_addc_u32 s7, s7, 0
	s_add_u32 s44, s96, 0x2d80000
	s_addc_u32 s45, s97, 0
	s_mul_i32 s4, s30, 0x20000
	s_movk_i32 s42, 0x400
	s_movk_i32 s46, 0x200
	s_movk_i32 s5, 0x100
	s_branch .Lp0_dec9_join

.Lp0_w7:
	s_waitcnt vmcnt(12)
	v_add_u32_e32 v68, 0x8200, v6
	ds_write2_b32 v68, v36, v37 offset1:1
	ds_write2_b32 v68, v38, v39 offset0:2 offset1:3
	v_add_u32_e32 v68, 0x8200, v7
	ds_write2_b32 v68, v40, v41 offset1:1
	ds_write2_b32 v68, v42, v43 offset0:2 offset1:3
	v_add_u32_e32 v68, 0x8200, v8
	ds_write2_b32 v68, v44, v45 offset1:1
	ds_write2_b32 v68, v46, v47 offset0:2 offset1:3
	v_add_u32_e32 v68, 0x8200, v9
	ds_write2_b32 v68, v48, v49 offset1:1
	ds_write2_b32 v68, v50, v51 offset0:2 offset1:3
	s_waitcnt lgkmcnt(0)
	s_barrier
	v_mul_lo_u32 v13, v4, s54
	v_lshl_add_u32 v13, v5, 4, v13
	s_lshl_b32 s4, s54, 5
	v_add_u32_e32 v83, 0x8200, v10
	ds_read_b32 v68, v83 offset:0
	ds_read_b32 v69, v83 offset:260
	ds_read_b32 v70, v83 offset:520
	ds_read_b32 v71, v83 offset:780
	ds_read_b32 v72, v83 offset:1040
	ds_read_b32 v73, v83 offset:1300
	ds_read_b32 v74, v83 offset:1560
	ds_read_b32 v75, v83 offset:1820
	s_waitcnt lgkmcnt(0)
	v_cvt_pk_bf16_f32 v84, v68, v69
	v_cvt_pk_bf16_f32 v85, v70, v71
	v_cvt_pk_bf16_f32 v86, v72, v73
	v_cvt_pk_bf16_f32 v87, v74, v75
	global_store_dwordx4 v13, v[84:87], s[52:53]
	v_add_u32_e32 v13, s4, v13
	v_add_u32_e32 v83, 0x8200, v11
	ds_read_b32 v68, v83 offset:0
	ds_read_b32 v69, v83 offset:260
	ds_read_b32 v70, v83 offset:520
	ds_read_b32 v71, v83 offset:780
	ds_read_b32 v72, v83 offset:1040
	ds_read_b32 v73, v83 offset:1300
	ds_read_b32 v74, v83 offset:1560
	ds_read_b32 v75, v83 offset:1820
	s_waitcnt lgkmcnt(0)
	v_cvt_pk_bf16_f32 v88, v68, v69
	v_cvt_pk_bf16_f32 v89, v70, v71
	v_cvt_pk_bf16_f32 v90, v72, v73
	v_cvt_pk_bf16_f32 v91, v74, v75
	global_store_dwordx4 v13, v[88:91], s[52:53]
	s_cmp_ge_u32 s36, s56
	s_cbranch_scc1 .Lp0_r7
	s_cmpk_ge_u32 s36, 0x5b8
	s_cselect_b32 s30, 1, 0
	s_mul_i32 s4, s30, 0x5b8
	s_sub_u32 s31, s36, s4
	s_cmpk_lt_u32 s31, 0x130
	s_cbranch_scc1 .Lp0_dec10_win
	s_cmpk_lt_u32 s31, 0x1b0
	s_cbranch_scc1 .Lp0_dec10_wout
	s_cmpk_lt_u32 s31, 0x3b0
	s_cbranch_scc1 .Lp0_dec10_w1
	s_cmpk_lt_u32 s31, 0x5b0
	s_cbranch_scc1 .Lp0_dec10_w2
	s_sub_u32 s31, s31, 0x5b0
	s_lshr_b32 s34, s31, 2
	s_and_b32 s35, s31, 3
	v_readlane_b32 s6, v237, 51
	v_readlane_b32 s7, v237, 52
	s_mul_i32 s4, s30, 0x40000
	s_add_u32 s6, s6, s4
	s_addc_u32 s7, s7, 0
	s_add_u32 s52, s96, 0x2d80000
	s_addc_u32 s53, s97, 0
	s_mul_i32 s4, s30, 0x20000
	s_movk_i32 s50, 0x400
	s_movk_i32 s54, 0x200
	s_movk_i32 s5, 0x100
	s_branch .Lp0_dec10_join

.Lp0_r7:
	s_sub_u32 s37, s37, 1
	s_cmp_eq_u32 s37, 0
	s_cbranch_scc1 .Lp0_done
	s_branch .Lp0_loop
.Lp0_done:
	s_waitcnt vmcnt(0) lgkmcnt(0)
	s_branch .LBB0_853
.LBB0_853:
	s_barrier

.LBB0_917:
	s_sleep 1
	global_load_dword v1, v2, s[36:37] offset:32 sc1
	s_waitcnt vmcnt(0)
	v_and_b32_e32 v1, 0xffff0000, v1
	v_cmp_ne_u32_e32 vcc, v1, v0
	s_or_b64 s[38:39], vcc, s[38:39]
	s_andn2_b64 exec, exec, s[38:39]
	s_cbranch_execnz .LBB0_917
	s_branch .LBB0_10
.LBB0_919:
	s_endpgm
